# MoBA: per-block K/V address setup skipped by waves that own no pair in the block (check moved ahead of the setup), on top of stride-8 pair dealing
# baseline (speedup 1.0000x reference)
.LBB0_1911:
	s_lshl_b32 s18, s74, 5
	s_add_i32 s18, s18, 0
	s_add_i32 s18, s18, 0x23000
	v_mov_b32_e32 v1, s18
	ds_read_b32 v2, v1
	s_waitcnt lgkmcnt(1)
	ds_read_b32 v3, v1 offset:4
	ds_read_b32 v4, v1 offset:8
	ds_read_b32 v5, v1 offset:12
	ds_read_b32 v6, v1 offset:16
	s_waitcnt lgkmcnt(3)
	v_add_u32_e32 v2, v3, v2
	s_waitcnt lgkmcnt(2)
	v_add_u32_e32 v2, v2, v4
	ds_read_b32 v3, v1 offset:20
	ds_read_b32 v4, v1 offset:24
	ds_read_b32 v1, v1 offset:28
	s_waitcnt lgkmcnt(4)
	v_add_u32_e32 v2, v2, v5
	s_waitcnt lgkmcnt(3)
	v_add_u32_e32 v2, v2, v6
	s_waitcnt lgkmcnt(2)
	v_add_u32_e32 v2, v2, v3
	s_waitcnt lgkmcnt(1)
	v_add_u32_e32 v2, v2, v4
	s_waitcnt lgkmcnt(0)
	v_add_u32_e32 v1, v2, v1
	s_nop 0
	v_readfirstlane_b32 s75, v1
	s_add_i32 s18, s75, 31
	s_ashr_i32 s77, s18, 5
	s_add_i32 s18, s77, 1
	s_ashr_i32 s76, s18, 1
	s_cmp_lt_i32 s76, 1
	s_cbranch_scc1 .LBB0_1910
	s_sub_i32 s79, s82, s28
	s_and_b32 s79, s79, 7
	s_cmp_ge_u32 s79, s76
	s_cbranch_scc1 .LBB0_1910
	v_lshl_or_b32 v166, s74, 8, v225
	v_lshl_add_u64 v[2:3], s[72:73], 0, v[166:167]
	v_lshlrev_b64 v[2:3], 11, v[2:3]
	v_lshlrev_b32_e32 v1, 1, v184
	v_or_b32_e32 v2, v2, v1
	v_lshl_add_u64 v[190:191], s[40:41], 0, v[2:3]
	v_lshl_add_u64 v[192:193], s[42:43], 0, v[2:3]
	v_or_b32_e32 v2, 8, v166
	v_mov_b32_e32 v3, v167
	v_lshl_add_u64 v[2:3], s[72:73], 0, v[2:3]
	v_lshlrev_b64 v[2:3], 11, v[2:3]
	v_or_b32_e32 v2, v2, v1
	v_lshl_add_u64 v[194:195], s[40:41], 0, v[2:3]
	v_lshl_add_u64 v[198:199], s[42:43], 0, v[2:3]
	v_or_b32_e32 v2, 16, v166
	v_mov_b32_e32 v3, v167
	v_lshl_add_u64 v[2:3], s[72:73], 0, v[2:3]
	v_lshlrev_b64 v[2:3], 11, v[2:3]
	v_or_b32_e32 v2, v2, v1
	v_lshl_add_u64 v[200:201], s[40:41], 0, v[2:3]
	v_lshl_add_u64 v[202:203], s[42:43], 0, v[2:3]
	v_or_b32_e32 v2, 24, v166
	v_mov_b32_e32 v3, v167
	v_lshl_add_u64 v[2:3], s[72:73], 0, v[2:3]
	v_lshlrev_b64 v[2:3], 11, v[2:3]
	v_or_b32_e32 v2, v2, v1
	v_lshl_add_u64 v[204:205], s[40:41], 0, v[2:3]
	v_lshl_add_u64 v[206:207], s[42:43], 0, v[2:3]
	v_or_b32_e32 v2, 32, v166
	v_mov_b32_e32 v3, v167
	v_lshl_add_u64 v[2:3], s[72:73], 0, v[2:3]
	v_lshlrev_b64 v[2:3], 11, v[2:3]
	v_or_b32_e32 v2, v2, v1
	v_lshl_add_u64 v[208:209], s[40:41], 0, v[2:3]
	v_lshl_add_u64 v[210:211], s[42:43], 0, v[2:3]
	v_or_b32_e32 v2, 40, v166
	v_mov_b32_e32 v3, v167
	v_lshl_add_u64 v[2:3], s[72:73], 0, v[2:3]
	v_lshlrev_b64 v[2:3], 11, v[2:3]
	v_or_b32_e32 v2, v2, v1
	v_lshl_add_u64 v[212:213], s[40:41], 0, v[2:3]
	v_lshl_add_u64 v[214:215], s[42:43], 0, v[2:3]
	v_or_b32_e32 v2, 48, v166
	v_mov_b32_e32 v3, v167
	v_lshl_add_u64 v[2:3], s[72:73], 0, v[2:3]
	v_lshlrev_b64 v[2:3], 11, v[2:3]
	v_or_b32_e32 v2, v2, v1
	v_or_b32_e32 v166, 56, v166
	v_lshl_add_u64 v[216:217], s[40:41], 0, v[2:3]
	v_lshl_add_u64 v[218:219], s[42:43], 0, v[2:3]
	v_lshl_add_u64 v[2:3], s[72:73], 0, v[166:167]
	s_lshl_b32 s18, s29, 2
	v_lshlrev_b64 v[2:3], 11, v[2:3]
	s_add_i32 s78, s18, 0
	v_or_b32_e32 v2, v2, v1
	s_add_i32 s77, s77, -1
	s_add_i32 s78, s78, 0x23200
	v_lshl_add_u64 v[220:221], s[40:41], 0, v[2:3]
	v_lshl_add_u64 v[222:223], s[42:43], 0, v[2:3]
	s_branch .LBB0_1915
